# v055 + out-proj / down-proj phases: the dummy last-iteration prefetch re-reads the unit's last two K-tiles (L2-hot) instead of its first two, shortening the post-loop drain
# baseline (speedup 1.0000x reference)
;     __host__ __device__ bool next(int i, Unit& u) const { Unit b; if (!base.next(i >> 1, b)) return false; u.pm = b.pm; u.pn = b.pn + 4 * (i & 1); return true; }
; template <class Epi, class Sched, bool ALIGN_EPI = false, bool SP2 = false, bool PAIR_ACC = false>
; __device__ __forceinline__ void gemm_phase(PG8_LAS unsigned char* lds, const Gemm g, const Sched& S, const Epi& E) {
;     ...
;         const bool has_next = S.next(ui + 1, nxt);
;         const char* nA = has_next ? (const char*)g.A + (size_t)nxt.pm * tstep + (size_t)(nxt.pn / g.a_div) * g.a_sel : cA; const char* nB = has_next ? (const char*)g.Bt + (size_t)nxt.pn * tstep : cB;
;         for (int t = 0; t < nt; t += 2) {
;             const bool last = (t == nt - 2);
;             const char* a1 = cA + (size_t)(t + 1) * kstep;
;             const char* a2 = last ? nA : cA + (size_t)(t + 2) * kstep; const char* b2 = last ? nB : cB + (size_t)(t + 2) * kstep;
;             const char* a3 = a2 + kstep; const char* b3 = b2 + kstep;
.LBB0_726:
	s_add_u32 s60, s52, 0x100
	s_addc_u32 s61, s53, 0
	s_ashr_i32 s43, s42, 31
	s_lshl_b64 s[38:39], s[42:43], 19
	s_add_u32 s50, s25, s38
	s_addc_u32 s51, s34, s39
	s_and_b64 s[38:39], s[8:9], exec
	s_cselect_b32 s43, s51, s21
	s_cselect_b32 s62, s50, s20
	s_cbranch_scc1 .Lhot_e0a
	s_add_u32 s62, s62, 0x700
	s_addc_u32 s43, s43, 0
.Lhot_e0a:
	s_ashr_i32 s31, s30, 31
	s_lshl_b64 s[38:39], s[30:31], 19
	s_add_u32 s48, s35, s38
	s_addc_u32 s49, s36, s39
	s_and_b64 s[38:39], s[8:9], exec
	s_cselect_b32 s31, s49, s53
	s_cselect_b32 s63, s48, s52
	s_cbranch_scc1 .Lhot_e0b
	s_add_u32 s63, s63, 0x700
	s_addc_u32 s31, s31, 0
.Lhot_e0b:
	v_lshl_add_u64 v[146:147], s[20:21], 0, v[138:139]
	v_lshl_add_u64 v[148:149], s[20:21], 0, v[140:141]
	s_mov_b32 s64, -2
	s_mov_b64 s[52:53], 0

;     __host__ __device__ bool next(int i, Unit& u) const { Unit b; if (!base.next(i >> 1, b)) return false; u.pm = b.pm; u.pn = b.pn + 4 * (i & 1); return true; }
; template <class Epi, class Sched, bool ALIGN_EPI = false, bool SP2 = false, bool PAIR_ACC = false>
; __device__ __forceinline__ void gemm_phase(PG8_LAS unsigned char* lds, const Gemm g, const Sched& S, const Epi& E) {
;     ...
;         const bool has_next = S.next(ui + 1, nxt);
;         const char* nA = has_next ? (const char*)g.A + (size_t)nxt.pm * tstep + (size_t)(nxt.pn / g.a_div) * g.a_sel : cA; const char* nB = has_next ? (const char*)g.Bt + (size_t)nxt.pn * tstep : cB;
.LBB0_932:
	v_cndmask_b32_e64 v146, 0, 1, s[10:11]
	v_cmp_ne_u32_e64 s[8:9], 1, v146
	s_andn2_b64 vcc, exec, s[10:11]
	s_mov_b64 s[48:49], s[28:29]
	s_add_u32 s48, s48, 0x1500
	s_addc_u32 s49, s49, 0
	s_cbranch_vccnz .LBB0_934
	s_mul_i32 s11, s55, 0x160000
	s_mul_hi_i32 s10, s55, 0x160000
	s_add_u32 s48, s20, s11
	s_addc_u32 s49, s21, s10
.LBB0_934:
	s_and_b64 vcc, exec, s[8:9]
	s_mov_b64 s[10:11], s[50:51]
	s_add_u32 s10, s10, 0x1500
	s_addc_u32 s11, s11, 0
	s_cbranch_vccnz .LBB0_936
	s_mul_i32 s10, s54, 0x160000
	s_mul_hi_i32 s11, s54, 0x160000
	s_add_u32 s10, s34, s10
	s_addc_u32 s11, s35, s11

;     __host__ __device__ bool next(int i, Unit& u) const { Unit b; if (!base.next(i >> 1, b)) return false; u.pm = b.pm; u.pn = b.pn + 4 * (i & 1); return true; }
; template <class Epi, class Sched, bool ALIGN_EPI = false, bool SP2 = false, bool PAIR_ACC = false>
; __device__ __forceinline__ void gemm_phase(PG8_LAS unsigned char* lds, const Gemm g, const Sched& S, const Epi& E) {
;     ...
;         const bool has_next = S.next(ui + 1, nxt);
;         const char* nA = has_next ? (const char*)g.A + (size_t)nxt.pm * tstep + (size_t)(nxt.pn / g.a_div) * g.a_sel : cA; const char* nB = has_next ? (const char*)g.Bt + (size_t)nxt.pn * tstep : cB;
;         for (int t = 0; t < nt; t += 2) {
;             const bool last = (t == nt - 2);
;             const char* a1 = cA + (size_t)(t + 1) * kstep;
;             const char* a2 = last ? nA : cA + (size_t)(t + 2) * kstep; const char* b2 = last ? nB : cB + (size_t)(t + 2) * kstep;
;             const char* a3 = a2 + kstep; const char* b3 = b2 + kstep;
.LBB0_1629:
	s_add_u32 s42, s44, 0x100
	s_addc_u32 s43, s45, 0
	s_ashr_i32 s31, s30, 31
	s_lshl_b64 s[38:39], s[30:31], 19
	s_add_u32 s40, s25, s38
	s_addc_u32 s41, s34, s39
	s_and_b64 s[38:39], s[8:9], exec
	s_cselect_b32 s31, s41, s21
	s_cselect_b32 s60, s40, s20
	s_cbranch_scc1 .Lhot_e1a
	s_add_u32 s60, s60, 0x700
	s_addc_u32 s31, s31, 0
.Lhot_e1a:
	s_ashr_i32 s29, s28, 31
	s_lshl_b64 s[38:39], s[28:29], 19
	s_add_u32 s38, s35, s38
	s_addc_u32 s39, s36, s39
	s_and_b64 s[46:47], s[8:9], exec
	s_cselect_b32 s29, s39, s45
	s_cselect_b32 s61, s38, s44
	s_cbranch_scc1 .Lhot_e1b
	s_add_u32 s61, s61, 0x700
	s_addc_u32 s29, s29, 0
.Lhot_e1b:
	v_lshl_add_u64 v[146:147], s[20:21], 0, v[138:139]
	v_lshl_add_u64 v[148:149], s[20:21], 0, v[140:141]
	s_mov_b32 s62, -2
	s_mov_b64 s[44:45], 0

;     __host__ __device__ bool next(int i, Unit& u) const { Unit b; if (!base.next(i >> 1, b)) return false; u.pm = b.pm; u.pn = b.pn + 4 * (i & 1); return true; }
; template <class Epi, class Sched, bool ALIGN_EPI = false, bool SP2 = false, bool PAIR_ACC = false>
; __device__ __forceinline__ void gemm_phase(PG8_LAS unsigned char* lds, const Gemm g, const Sched& S, const Epi& E) {
;     ...
;         const bool has_next = S.next(ui + 1, nxt);
;         const char* nA = has_next ? (const char*)g.A + (size_t)nxt.pm * tstep + (size_t)(nxt.pn / g.a_div) * g.a_sel : cA; const char* nB = has_next ? (const char*)g.Bt + (size_t)nxt.pn * tstep : cB;
.LBB0_1835:
	v_cndmask_b32_e64 v146, 0, 1, s[4:5]
	v_cmp_ne_u32_e64 s[6:7], 1, v146
	s_andn2_b64 vcc, exec, s[4:5]
	s_mov_b64 s[22:23], s[18:19]
	s_add_u32 s22, s22, 0x1500
	s_addc_u32 s23, s23, 0
	s_cbranch_vccnz .LBB0_1837
	s_mul_i32 s5, s48, 0x160000
	s_mul_hi_i32 s4, s48, 0x160000
	s_add_u32 s22, s16, s5
	s_addc_u32 s23, s17, s4
.LBB0_1837:
	s_and_b64 vcc, exec, s[6:7]
	s_mov_b64 s[4:5], s[24:25]
	s_add_u32 s4, s4, 0x1500
	s_addc_u32 s5, s5, 0
	s_cbranch_vccnz .LBB0_1839
	s_mul_i32 s4, s47, 0x160000
	s_mul_hi_i32 s5, s47, 0x160000
	s_add_u32 s4, s35, s4
	s_addc_u32 s5, s36, s5
